# NA mask folded into rpb lookup address (filler region) + QK accumulates directly in softmax registers (no per-tile copies)
# speedup vs baseline: 1.0046x; 1.0046x over previous
; #define LAS __attribute__((address_space(3)))
; template <int DQ>
; __device__ __forceinline__ void attn_unit(LAS unsigned char* lds, const AttnDesc& A, int tid_in, int wid, int lane_in) {
;     constexpr int KSTR = (DQ + 8) * 2, NS = DQ / 16;
;     int tid = tid_in; asm volatile("" : "+v"(tid));
;     const int lane = tid & 63; (void)lane_in;
;     const int r32 = lane & 31, h = lane >> 5;
;     const int nt = A.nloc + 4;
;     bf16x8 qf[NS];
; #pragma unroll
;     for (int s = 0; s < NS; ++s) qf[s] = *(const bf16x8*)(A.q + (size_t)r32 * A.ldq + 16 * s + 8 * h);
;     f32x16 o0, o1;
; #pragma unroll
;     for (int r = 0; r < 16; ++r) { o0[r] = 0.f; o1[r] = 0.f; }
;     float mrun = -1e30f, lrun = 0.f;
;     f32x16 zero16;
; #pragma unroll
;     for (int r = 0; r < 16; ++r) zero16[r] = 0.f;
;     asm volatile("" : "+v"(zero16));
;     const int skey = tid >> 3, sch = tid & 7;
;     u32x4 kreg, vreg, krreg = (u32x4){0u, 0u, 0u, 0u};
;     {
;         const int row0 = (0 < A.nloc) ? A.loc_row0 : A.ctx_row0;
;         kreg = *(const u32x4*)(A.k + (size_t)(row0 + skey) * A.ldk + 8 * sch);
;         vreg = *(const u32x4*)(A.v + (size_t)(row0 + skey) * A.ldv + 8 * sch);
;         if (DQ == 96 && tid < 256) krreg = *(const u32x4*)(A.kr + (size_t)(row0 + (tid >> 2)) * A.ldkr + 8 * (tid & 3));
;     }
;     const LAS float* rpbl = (const LAS float*)(lds + ATT_RPB);
;     const int vtr_off = ((lane & 15) >> 2) * 64 + (16 * ((lane >> 4) & 1) + 4 * (lane & 3)) * 2 + 4 * h * 64;
;     ...
;                 const int qc = 32 * (wid & 1) + r32;
;                 const int w0 = min(max(qc - 8, 0), 48);
;                 const int rbase = (A.a0 + t - A.a1 + 7) * 31;
; #pragma unroll
;                 for (int r = 0; r < 16; ++r) {
;                     const int kc = (r & 3) + 8 * (r >> 2) + 4 * h;
;                     { const int dc = min(max(kc - qc + 15, 0), 30); const bool ok = (unsigned)(kc - w0) < 16u; const float bv = rpbl[rbase + dc]; s0[r] = ok ? s0[r] + bv : -1e30f; }
.LBB0_54:
	v_mov_b32_e32 v32, v154
	v_mov_b32_e32 v157, v1
	v_and_b32_e32 v165, 31, v32
	v_mul_u32_u24_e32 v0, s40, v165
	v_bfe_u32 v33, v32, 5, 1
	v_lshlrev_b32_e32 v0, 1, v0
	v_lshl_add_u64 v[2:3], s[0:1], 0, v[0:1]
	v_lshlrev_b32_e32 v156, 4, v33
	v_lshl_add_u64 v[2:3], v[2:3], 0, v[156:157]
	s_waitcnt vmcnt(0)
	flat_load_dwordx4 v[130:133], v[2:3]
	flat_load_dwordx4 v[134:137], v[2:3] offset:32
	flat_load_dwordx4 v[138:141], v[2:3] offset:64
	flat_load_dwordx4 v[142:145], v[2:3] offset:96
	v_mov_b32_e32 v14, v1
	v_mov_b32_e32 v15, v1
	v_mov_b32_e32 v0, v1
	v_mov_b32_e32 v2, v1
	v_mov_b32_e32 v3, v1
	v_mov_b32_e32 v4, v1
	v_mov_b32_e32 v5, v1
	v_mov_b32_e32 v6, v1
	v_mov_b32_e32 v7, v1
	v_mov_b32_e32 v8, v1
	v_mov_b32_e32 v9, v1
	v_mov_b32_e32 v10, v1
	v_mov_b32_e32 v11, v1
	v_mov_b32_e32 v12, v1
	v_mov_b32_e32 v13, v1
	v_mov_b64_e32 v[30:31], v[14:15]
	v_mov_b64_e32 v[28:29], v[12:13]
	v_mov_b64_e32 v[26:27], v[10:11]
	v_mov_b64_e32 v[24:25], v[8:9]
	v_mov_b64_e32 v[22:23], v[6:7]
	v_mov_b64_e32 v[20:21], v[4:5]
	v_mov_b64_e32 v[18:19], v[2:3]
	v_mov_b64_e32 v[16:17], v[0:1]
	s_mov_b32 s41, 0
	s_cmp_lt_i32 s59, -3
	v_lshlrev_b32_e32 v157, 2, v33
	s_cbranch_scc1 .LBB0_137
	s_lshl_b32 s60, s8, 8
	s_add_i32 s56, s59, 4
	s_add_i32 s60, s60, 0x8000
	v_ashrrev_i32_e32 v38, 3, v32
	v_lshlrev_b32_e32 v39, 4, v32
	v_and_b32_e32 v34, 16, v32
	v_lshlrev_b32_e32 v35, 2, v32
	s_cmp_gt_i32 s59, 0
	v_lshlrev_b32_e32 v32, 10, v32
	s_cselect_b32 s0, s57, s60
	v_and_b32_e32 v174, 0x1000, v32
	v_or_b32_e32 v32, s22, v165
	v_and_or_b32 v34, v35, 12, v34
	v_lshlrev_b32_e32 v172, 8, v33
	v_add_u32_e32 v33, s0, v38
	v_sub_u32_e64 v32, v32, 8 clamp
	v_lshlrev_b32_e32 v171, 1, v34
	v_mad_i64_i32 v[34:35], s[0:1], s40, v33, 0
	v_min_u32_e32 v32, 48, v32
	v_or_b32_e32 v33, 1, v157
	v_lshlrev_b64 v[34:35], 1, v[34:35]
	s_movk_i32 s0, 0x90
	v_sub_u32_e32 v33, v33, v32
	v_lshl_add_u64 v[36:37], s[50:51], 0, v[34:35]
	v_and_b32_e32 v158, 0x70, v39
	v_mov_b32_e32 v159, v1
	v_lshl_add_u64 v[34:35], s[48:49], 0, v[34:35]
	v_mul_lo_u32 v173, v38, s0
	v_cmp_gt_u32_e64 s[0:1], 16, v33
	v_or_b32_e32 v33, 33, v157
	v_lshl_add_u64 v[34:35], v[34:35], 0, v[158:159]
	v_writelane_b32 v255, s0, 12
	v_sub_u32_e32 v33, v33, v32
	flat_load_dwordx4 v[150:153], v[34:35]
	v_or_b32_e32 v34, 2, v157
	v_writelane_b32 v255, s1, 13
	v_cmp_gt_u32_e64 s[0:1], 16, v33
	v_sub_u32_e32 v33, v34, v32
	v_or_b32_e32 v35, 3, v157
	v_writelane_b32 v255, s0, 14
	v_lshl_add_u64 v[36:37], v[36:37], 0, v[158:159]
	flat_load_dwordx4 v[146:149], v[36:37]
	v_writelane_b32 v255, s1, 15
	v_cmp_gt_u32_e64 s[0:1], 16, v33
	v_or_b32_e32 v33, 34, v157
	v_sub_u32_e32 v33, v33, v32
	v_writelane_b32 v255, s0, 16
	v_or_b32_e32 v36, 8, v157
	v_or_b32_e32 v37, 9, v157
	v_writelane_b32 v255, s1, 17
	v_cmp_gt_u32_e64 s[0:1], 16, v33
	v_sub_u32_e32 v33, v35, v32
	v_and_b32_e32 v65, 0xc0, v39
	v_writelane_b32 v255, s0, 18
	v_and_b32_e32 v176, 48, v39
	v_or_b32_e32 v39, 10, v157
	v_writelane_b32 v255, s1, 19
	v_cmp_gt_u32_e64 s[0:1], 16, v33
	v_or_b32_e32 v33, 35, v157
	v_sub_u32_e32 v33, v33, v32
	v_writelane_b32 v255, s0, 20
	v_or_b32_e32 v40, 11, v157
	v_or_b32_e32 v41, 16, v157
	v_writelane_b32 v255, s1, 21
	v_cmp_gt_u32_e64 s[0:1], 16, v33
	v_sub_u32_e32 v33, v36, v32
	v_or_b32_e32 v42, 17, v157
	v_writelane_b32 v255, s0, 22
	v_or_b32_e32 v43, 18, v157
	v_or_b32_e32 v44, 19, v157
	v_writelane_b32 v255, s1, 23
	v_cmp_gt_u32_e64 s[0:1], 16, v33
	v_or_b32_e32 v33, 40, v157
	v_sub_u32_e32 v33, v33, v32
	v_writelane_b32 v255, s0, 24
	v_or_b32_e32 v45, 24, v157
	s_mov_b64 s[68:69], s[92:93]
	v_writelane_b32 v255, s1, 25
	v_cmp_gt_u32_e64 s[0:1], 16, v33
	v_sub_u32_e32 v33, v37, v32
	v_or_b32_e32 v46, 25, v157
	v_writelane_b32 v255, s0, 26
	s_mov_b64 s[70:71], s[94:95]
	v_or_b32_e32 v47, 26, v157
	v_writelane_b32 v255, s1, 27
	v_cmp_gt_u32_e64 s[0:1], 16, v33
	v_or_b32_e32 v33, 41, v157
	v_sub_u32_e32 v33, v33, v32
	v_writelane_b32 v255, s0, 28
	s_mov_b64 s[64:65], s[98:99]
	v_or_b32_e32 v48, 27, v157
	v_writelane_b32 v255, s1, 29
	v_cmp_gt_u32_e64 s[0:1], 16, v33
	v_sub_u32_e32 v33, v39, v32
	v_sub_u32_e32 v49, v157, v32
	v_writelane_b32 v255, s0, 30
	v_cmp_gt_u32_e64 s[72:73], 16, v49
	v_or_b32_e32 v49, 32, v157
	v_writelane_b32 v255, s1, 31
	v_cmp_gt_u32_e64 s[0:1], 16, v33
	v_or_b32_e32 v33, 42, v157
	v_sub_u32_e32 v33, v33, v32
	v_writelane_b32 v255, s0, 32
	s_cmp_eq_u32 s53, 1
	v_sub_u32_e32 v49, v49, v32
	v_writelane_b32 v255, s1, 33
	v_cmp_gt_u32_e64 s[0:1], 16, v33
	v_sub_u32_e32 v33, v40, v32
	s_cselect_b64 s[84:85], -1, 0
	v_writelane_b32 v255, s0, 34
	s_add_i32 s58, s61, 8
	s_cmp_eq_u32 s53, 2
	v_writelane_b32 v255, s1, 35
	v_cmp_gt_u32_e64 s[0:1], 16, v33
	v_or_b32_e32 v33, 43, v157
	v_sub_u32_e32 v33, v33, v32
	v_writelane_b32 v255, s0, 36
	v_readlane_b32 s18, v254, 50
	v_lshl_add_u64 v[160:161], s[48:49], 0, v[158:159]
	v_writelane_b32 v255, s1, 37
	v_cmp_gt_u32_e64 s[0:1], 16, v33
	v_sub_u32_e32 v33, v41, v32
	v_lshl_add_u64 v[162:163], s[50:51], 0, v[158:159]
	v_writelane_b32 v255, s0, 38
	s_cselect_b64 s[86:87], -1, 0
	s_add_i32 s63, s52, 0xffffff9f
	v_writelane_b32 v255, s1, 39
	v_cmp_gt_u32_e64 s[0:1], 16, v33
	v_or_b32_e32 v33, 48, v157
	v_sub_u32_e32 v33, v33, v32
	v_writelane_b32 v255, s0, 40
	s_add_i32 s80, s52, 0x41
	v_lshlrev_b32_e32 v175, 6, v38
	v_writelane_b32 v255, s1, 41
	v_cmp_gt_u32_e64 s[0:1], 16, v33
	v_sub_u32_e32 v33, v42, v32
	v_cmp_gt_u32_e64 s[74:75], 16, v49
	v_writelane_b32 v255, s0, 42
	v_add_u32_e32 v211, 64, v38
	v_mul_u32_u24_e32 v177, 0x90, v165
	v_writelane_b32 v255, s1, 43
	v_cmp_gt_u32_e64 s[0:1], 16, v33
	v_or_b32_e32 v33, 49, v157
	v_sub_u32_e32 v33, v33, v32
; template <int DQ>
; __device__ __forceinline__ void attn_unit(LAS unsigned char* lds, const AttnDesc& A, int tid_in, int wid, int lane_in) {
;     ...
;                 const int qc = 32 * (wid & 1) + r32;
;                 const int w0 = min(max(qc - 8, 0), 48);
;                 const int rbase = (A.a0 + t - A.a1 + 7) * 31;
; #pragma unroll
;                 for (int r = 0; r < 16; ++r) {
;                     const int kc = (r & 3) + 8 * (r >> 2) + 4 * h;
;                     { const int dc = min(max(kc - qc + 15, 0), 30); const bool ok = (unsigned)(kc - w0) < 16u; const float bv = rpbl[rbase + dc]; s0[r] = ok ? s0[r] + bv : -1e30f; }
;                     { const int kc2 = kc + 32; const int dc = min(max(kc2 - qc + 15, 0), 30); const bool ok = (unsigned)(kc2 - w0) < 16u; const float bv = rpbl[rbase + dc]; s1[r] = ok ? s1[r] + bv : -1e30f; }
;                 }
	v_writelane_b32 v255, s0, 44
	v_mov_b32_e32 v212, 0xf149f2ca
	v_mov_b32_e32 v213, 0xf149f2ca
	v_mov_b32_e32 v64, 0
	v_writelane_b32 v255, s1, 45
	v_cmp_gt_u32_e64 s[0:1], 16, v33
	v_sub_u32_e32 v33, v43, v32
	s_mov_b32 s82, 0
	v_writelane_b32 v255, s0, 46
	s_nop 1
	v_writelane_b32 v255, s1, 47
	v_cmp_gt_u32_e64 s[0:1], 16, v33
	v_or_b32_e32 v33, 50, v157
	v_sub_u32_e32 v33, v33, v32
	v_writelane_b32 v255, s0, 48
	s_nop 1
	v_writelane_b32 v255, s1, 49
	v_cmp_gt_u32_e64 s[0:1], 16, v33
	v_sub_u32_e32 v33, v44, v32
	v_cmp_gt_u32_e64 s[88:89], 16, v33
	v_or_b32_e32 v33, 51, v157
	v_sub_u32_e32 v33, v33, v32
	v_cmp_gt_u32_e64 s[90:91], 16, v33
	v_sub_u32_e32 v33, v45, v32
	v_cmp_gt_u32_e64 s[92:93], 16, v33
	v_or_b32_e32 v33, 56, v157
	v_sub_u32_e32 v33, v33, v32
	v_cmp_gt_u32_e64 s[94:95], 16, v33
	v_sub_u32_e32 v33, v46, v32
	v_cmp_gt_u32_e64 s[96:97], 16, v33
	v_or_b32_e32 v33, 57, v157
	v_sub_u32_e32 v33, v33, v32
	v_writelane_b32 v255, s0, 50
	v_cmp_gt_u32_e64 s[98:99], 16, v33
	v_sub_u32_e32 v33, v47, v32
	v_writelane_b32 v255, s1, 51
	v_cmp_gt_u32_e64 s[0:1], 16, v33
	v_or_b32_e32 v33, 58, v157
	v_sub_u32_e32 v33, v33, v32
	v_cmp_gt_u32_e64 s[4:5], 16, v33
	v_sub_u32_e32 v33, v48, v32
	v_cmp_gt_u32_e64 s[6:7], 16, v33
	v_or_b32_e32 v33, 59, v157
	v_sub_u32_e32 v32, v33, v32
	v_cmp_gt_u32_e64 s[8:9], 16, v32
	v_add_u32_e32 v32, s52, v165
	v_sub_u32_e32 v159, v157, v32
	v_add_u32_e32 v32, s18, v157
	s_mul_i32 s18, s55, 0x7c
	s_mulk_i32 s52, 0x7c
	v_sub_u32_e32 v32, v32, v165
	s_sub_i32 s18, s18, s52
	v_max_i32_e32 v32, -15, v32
	s_add_i32 s81, s18, 0
	v_readlane_b32 s18, v254, 51
	v_lshlrev_b32_e32 v178, 2, v32
	v_mov_b64_e32 v[62:63], v[14:15]
	v_add_u32_e32 v32, s18, v157
	v_sub_u32_e32 v32, v32, v165
	v_max_i32_e32 v32, -15, v32
	v_add_u32_e32 v32, 15, v32
	v_min_u32_e32 v32, 30, v32
	v_readlane_b32 s18, v254, 52
	v_lshlrev_b32_e32 v179, 2, v32
	v_mov_b64_e32 v[60:61], v[12:13]
	v_add_u32_e32 v32, s18, v157
	v_sub_u32_e32 v32, v32, v165
	v_max_i32_e32 v32, -15, v32
	v_readlane_b32 s18, v254, 53
	v_lshlrev_b32_e32 v180, 2, v32
	v_mov_b64_e32 v[58:59], v[10:11]
	v_add_u32_e32 v32, s18, v157
	v_sub_u32_e32 v32, v32, v165
	v_max_i32_e32 v32, -15, v32
	v_add_u32_e32 v32, 15, v32
	v_min_u32_e32 v32, 30, v32
	v_readlane_b32 s18, v254, 54
	v_lshlrev_b32_e32 v182, 2, v32
	v_mov_b64_e32 v[56:57], v[8:9]
	v_add_u32_e32 v32, s18, v157
	v_sub_u32_e32 v32, v32, v165
	v_max_i32_e32 v32, -15, v32
	v_readlane_b32 s18, v254, 55
	v_lshlrev_b32_e32 v183, 2, v32
	v_mov_b64_e32 v[54:55], v[6:7]
	v_add_u32_e32 v32, s18, v157
	v_sub_u32_e32 v32, v32, v165
	v_max_i32_e32 v32, -15, v32
	v_add_u32_e32 v32, 15, v32
	v_min_u32_e32 v32, 30, v32
	v_readlane_b32 s18, v254, 56
	v_lshlrev_b32_e32 v184, 2, v32
	v_mov_b64_e32 v[52:53], v[4:5]
	v_add_u32_e32 v32, s18, v157
	v_sub_u32_e32 v32, v32, v165
	v_max_i32_e32 v32, -15, v32
	v_readlane_b32 s18, v254, 57
	v_lshlrev_b32_e32 v185, 2, v32
	v_mov_b64_e32 v[50:51], v[2:3]
	v_add_u32_e32 v32, s18, v157
	v_sub_u32_e32 v32, v32, v165
	v_max_i32_e32 v32, -15, v32
	v_add_u32_e32 v32, 15, v32
	v_min_u32_e32 v32, 30, v32
	v_readlane_b32 s18, v254, 58
	v_lshlrev_b32_e32 v186, 2, v32
	v_mov_b64_e32 v[48:49], v[0:1]
	v_add_u32_e32 v32, s18, v157
	v_sub_u32_e32 v32, v32, v165
	v_max_i32_e32 v32, -15, v32
	v_readlane_b32 s18, v254, 59
	v_lshlrev_b32_e32 v187, 2, v32
	s_nop 0
	v_add_u32_e32 v32, s18, v157
	v_sub_u32_e32 v32, v32, v165
	v_max_i32_e32 v32, -15, v32
	v_add_u32_e32 v32, 15, v32
	v_min_u32_e32 v32, 30, v32
	v_readlane_b32 s18, v254, 60
	v_lshlrev_b32_e32 v188, 2, v32
	s_nop 0
	v_add_u32_e32 v32, s18, v157
	v_sub_u32_e32 v32, v32, v165
	v_max_i32_e32 v32, -15, v32
	v_readlane_b32 s18, v254, 61
	v_lshlrev_b32_e32 v189, 2, v32
	s_nop 0
	v_add_u32_e32 v32, s18, v157
	v_sub_u32_e32 v32, v32, v165
	v_max_i32_e32 v32, -15, v32
	v_add_u32_e32 v32, 15, v32
	v_min_u32_e32 v32, 30, v32
	v_readlane_b32 s18, v254, 62
	v_lshlrev_b32_e32 v190, 2, v32
	s_nop 0
	v_add_u32_e32 v32, s18, v157
	v_sub_u32_e32 v32, v32, v165
	v_max_i32_e32 v32, -15, v32
	v_readlane_b32 s18, v254, 63
	v_lshlrev_b32_e32 v191, 2, v32
	s_nop 0
	v_add_u32_e32 v32, s18, v157
	v_sub_u32_e32 v32, v32, v165
	v_max_i32_e32 v32, -15, v32
	v_add_u32_e32 v32, 15, v32
	v_min_u32_e32 v32, 30, v32
	v_readlane_b32 s18, v255, 0
	v_lshlrev_b32_e32 v192, 2, v32
	s_nop 0
	v_add_u32_e32 v32, s18, v157
	v_sub_u32_e32 v32, v32, v165
	v_max_i32_e32 v32, -15, v32
	v_readlane_b32 s18, v255, 1
	v_lshlrev_b32_e32 v193, 2, v32
	s_nop 0
	v_add_u32_e32 v32, s18, v157
	v_sub_u32_e32 v32, v32, v165
	v_max_i32_e32 v32, -15, v32
	v_add_u32_e32 v32, 15, v32
	v_min_u32_e32 v32, 30, v32
	v_readlane_b32 s18, v255, 2
	v_lshlrev_b32_e32 v194, 2, v32
	s_nop 0
	v_add_u32_e32 v32, s18, v157
	v_sub_u32_e32 v32, v32, v165
	v_max_i32_e32 v32, -15, v32
	v_add_u32_e32 v32, 15, v32
	v_min_u32_e32 v32, 30, v32
	v_readlane_b32 s18, v255, 3
	v_lshlrev_b32_e32 v195, 2, v32
	s_nop 0
	v_add_u32_e32 v32, s18, v157
	v_sub_u32_e32 v32, v32, v165
	v_min_u32_e32 v32, 30, v32
	v_readlane_b32 s18, v255, 4
	v_lshlrev_b32_e32 v196, 2, v32
	s_nop 0
	v_add_u32_e32 v32, s18, v157
	v_sub_u32_e32 v32, v32, v165
	v_max_i32_e32 v32, -15, v32
	v_add_u32_e32 v32, 15, v32
	v_min_u32_e32 v32, 30, v32
	v_readlane_b32 s18, v255, 5
	v_lshlrev_b32_e32 v197, 2, v32
; template <int DQ>
; __device__ __forceinline__ void attn_unit(LAS unsigned char* lds, const AttnDesc& A, int tid_in, int wid, int lane_in) {
;     ...
;                 const int qc = 32 * (wid & 1) + r32;
;                 const int w0 = min(max(qc - 8, 0), 48);
;                 const int rbase = (A.a0 + t - A.a1 + 7) * 31;
; #pragma unroll
;                 for (int r = 0; r < 16; ++r) {
;                     const int kc = (r & 3) + 8 * (r >> 2) + 4 * h;
;                     { const int dc = min(max(kc - qc + 15, 0), 30); const bool ok = (unsigned)(kc - w0) < 16u; const float bv = rpbl[rbase + dc]; s0[r] = ok ? s0[r] + bv : -1e30f; }
;                     { const int kc2 = kc + 32; const int dc = min(max(kc2 - qc + 15, 0), 30); const bool ok = (unsigned)(kc2 - w0) < 16u; const float bv = rpbl[rbase + dc]; s1[r] = ok ? s1[r] + bv : -1e30f; }
;                 }
	s_nop 0
	v_add_u32_e32 v32, s18, v157
	v_sub_u32_e32 v32, v32, v165
	v_min_u32_e32 v32, 30, v32
	v_readlane_b32 s18, v255, 6
	v_lshlrev_b32_e32 v198, 2, v32
	s_nop 0
	v_add_u32_e32 v32, s18, v157
	v_sub_u32_e32 v32, v32, v165
	v_max_i32_e32 v32, -15, v32
	v_add_u32_e32 v32, 15, v32
	v_min_u32_e32 v32, 30, v32
	v_readlane_b32 s18, v255, 7
	v_lshlrev_b32_e32 v199, 2, v32
	s_nop 0
	v_add_u32_e32 v32, s18, v157
	v_sub_u32_e32 v32, v32, v165
	v_min_u32_e32 v32, 30, v32
	v_readlane_b32 s18, v255, 8
	v_lshlrev_b32_e32 v200, 2, v32
	s_nop 0
	v_add_u32_e32 v32, s18, v157
	v_sub_u32_e32 v32, v32, v165
	v_max_i32_e32 v32, -15, v32
	v_add_u32_e32 v32, 15, v32
	v_min_u32_e32 v32, 30, v32
	v_readlane_b32 s18, v255, 9
	v_lshlrev_b32_e32 v201, 2, v32
	s_nop 0
	v_add_u32_e32 v32, s18, v157
	v_sub_u32_e32 v32, v32, v165
	v_min_u32_e32 v32, 30, v32
	v_lshlrev_b32_e32 v202, 2, v32
	v_add_u32_e32 v32, s21, v157
	v_sub_u32_e32 v32, v32, v165
	v_max_i32_e32 v32, -15, v32
	v_add_u32_e32 v32, 15, v32
	v_min_u32_e32 v32, 30, v32
	v_lshlrev_b32_e32 v203, 2, v32
	v_add_u32_e32 v32, s23, v157
	v_sub_u32_e32 v32, v32, v165
	v_min_u32_e32 v32, 30, v32
	v_lshlrev_b32_e32 v204, 2, v32
	v_add_u32_e32 v32, s24, v157
	v_sub_u32_e32 v32, v32, v165
	v_max_i32_e32 v32, -15, v32
	v_add_u32_e32 v32, 15, v32
	v_min_u32_e32 v32, 30, v32
	v_lshlrev_b32_e32 v205, 2, v32
	v_add_u32_e32 v32, s25, v157
	v_sub_u32_e32 v32, v32, v165
	v_min_u32_e32 v32, 30, v32
	v_lshlrev_b32_e32 v206, 2, v32
	v_add_u32_e32 v32, s26, v157
	v_sub_u32_e32 v32, v32, v165
	v_max_i32_e32 v32, -15, v32
	v_add_u32_e32 v32, 15, v32
	v_min_u32_e32 v32, 30, v32
	v_lshlrev_b32_e32 v207, 2, v32
	v_add_u32_e32 v32, s27, v157
	v_sub_u32_e32 v32, v32, v165
	v_min_u32_e32 v32, 30, v32
	v_lshlrev_b32_e32 v208, 2, v32
	v_add_u32_e32 v32, s31, v157
	v_sub_u32_e32 v32, v32, v165
	v_max_i32_e32 v32, -15, v32
	v_add_u32_e32 v32, 15, v32
	v_min_u32_e32 v32, 30, v32
	v_lshlrev_b32_e32 v209, 2, v32
	v_add_u32_e32 v32, s46, v157
	v_sub_u32_e32 v32, v32, v165
	v_min_u32_e32 v32, 30, v32
	v_lshlrev_b32_e32 v210, 2, v32
	v_mov_b64_e32 v[46:47], v[14:15]
	v_mov_b64_e32 v[44:45], v[12:13]
	v_mov_b64_e32 v[42:43], v[10:11]
	v_mov_b64_e32 v[40:41], v[8:9]
	v_mov_b64_e32 v[38:39], v[6:7]
	v_mov_b64_e32 v[36:37], v[4:5]
	v_mov_b64_e32 v[34:35], v[2:3]
	v_mov_b64_e32 v[32:33], v[0:1]
	v_min_u32_e32 v0, 464, v236
	v_lshlrev_b32_e32 v0, 2, v0
	ds_write_b32 v0, v241 offset:44868
	v_mov_b32_e32 v2, 1800
	v_mov_b32_e32 v3, 1860
	v_cndmask_b32_e64 v178, v2, v178, s[72:73]
	v_cndmask_b32_e64 v179, v3, v179, s[74:75]
	v_readlane_b32 s50, v255, 12
	v_readlane_b32 s51, v255, 13
	s_nop 1
	v_cndmask_b32_e64 v180, v2, v180, s[50:51]
	v_readlane_b32 s50, v255, 14
	v_readlane_b32 s51, v255, 15
	s_nop 1
	v_cndmask_b32_e64 v182, v3, v182, s[50:51]
	v_readlane_b32 s50, v255, 16
	v_readlane_b32 s51, v255, 17
	s_nop 1
	v_cndmask_b32_e64 v183, v2, v183, s[50:51]
	v_readlane_b32 s50, v255, 18
	v_readlane_b32 s51, v255, 19
	s_nop 1
	v_cndmask_b32_e64 v184, v3, v184, s[50:51]
	v_readlane_b32 s50, v255, 20
	v_readlane_b32 s51, v255, 21
	s_nop 1
	v_cndmask_b32_e64 v185, v2, v185, s[50:51]
	v_readlane_b32 s50, v255, 22
	v_readlane_b32 s51, v255, 23
	s_nop 1
	v_cndmask_b32_e64 v186, v3, v186, s[50:51]
	v_readlane_b32 s50, v255, 24
	v_readlane_b32 s51, v255, 25
	s_nop 1
	v_cndmask_b32_e64 v187, v2, v187, s[50:51]
	v_readlane_b32 s50, v255, 26
	v_readlane_b32 s51, v255, 27
	s_nop 1
	v_cndmask_b32_e64 v188, v3, v188, s[50:51]
	v_readlane_b32 s50, v255, 28
	v_readlane_b32 s51, v255, 29
	s_nop 1
	v_cndmask_b32_e64 v189, v2, v189, s[50:51]
	v_readlane_b32 s50, v255, 30
	v_readlane_b32 s51, v255, 31
	s_nop 1
	v_cndmask_b32_e64 v190, v3, v190, s[50:51]
	v_readlane_b32 s50, v255, 32
	v_readlane_b32 s51, v255, 33
	s_nop 1
	v_cndmask_b32_e64 v191, v2, v191, s[50:51]
	v_readlane_b32 s50, v255, 34
	v_readlane_b32 s51, v255, 35
	s_nop 1
	v_cndmask_b32_e64 v192, v3, v192, s[50:51]
	v_readlane_b32 s50, v255, 36
	v_readlane_b32 s51, v255, 37
	s_nop 1
	v_cndmask_b32_e64 v193, v2, v193, s[50:51]
	v_readlane_b32 s50, v255, 38
	v_readlane_b32 s51, v255, 39
	s_nop 1
	v_cndmask_b32_e64 v194, v3, v194, s[50:51]
	v_readlane_b32 s50, v255, 40
	v_readlane_b32 s51, v255, 41
	s_nop 1
	v_cndmask_b32_e64 v195, v3, v195, s[50:51]
	v_readlane_b32 s50, v255, 42
	v_readlane_b32 s51, v255, 43
	s_nop 1
	v_cndmask_b32_e64 v196, v3, v196, s[50:51]
	v_readlane_b32 s50, v255, 44
	v_readlane_b32 s51, v255, 45
	s_nop 1
	v_cndmask_b32_e64 v197, v3, v197, s[50:51]
	v_readlane_b32 s50, v255, 46
	v_readlane_b32 s51, v255, 47
	s_nop 1
	v_cndmask_b32_e64 v198, v3, v198, s[50:51]
	v_readlane_b32 s50, v255, 48
	v_readlane_b32 s51, v255, 49
	s_nop 1
	v_cndmask_b32_e64 v199, v3, v199, s[50:51]
	v_readlane_b32 s50, v255, 50
	v_readlane_b32 s51, v255, 51
	s_nop 1
	v_cndmask_b32_e64 v200, v3, v200, s[50:51]
	v_cndmask_b32_e64 v201, v3, v201, s[88:89]
	v_cndmask_b32_e64 v202, v3, v202, s[90:91]
	v_cndmask_b32_e64 v203, v3, v203, s[92:93]
	v_cndmask_b32_e64 v204, v3, v204, s[94:95]
	v_cndmask_b32_e64 v205, v3, v205, s[96:97]
	v_cndmask_b32_e64 v206, v3, v206, s[98:99]
	v_cndmask_b32_e64 v207, v3, v207, s[0:1]
	v_cndmask_b32_e64 v208, v3, v208, s[4:5]
	v_cndmask_b32_e64 v209, v3, v209, s[6:7]
	v_cndmask_b32_e64 v210, v3, v210, s[8:9]

; #define LAS __attribute__((address_space(3)))
; template <int DQ>
; __device__ __forceinline__ void attn_unit(LAS unsigned char* lds, const AttnDesc& A, int tid_in, int wid, int lane_in) {
;     ...
;             kq[0][0] = *(const LAS bf16x8*)(kb + r32 * KSTR + (8 * h) * 2); kq[0][1] = *(const LAS bf16x8*)(kb + (32 + r32) * KSTR + (8 * h) * 2);
;             __builtin_amdgcn_sched_group_barrier(0x100, 2, 0);
; #pragma unroll
;             for (int s = 0; s < NS; ++s) {
;                 if (s + 1 < NS) {
;                     kq[(s + 1) & 1][0] = *(const LAS bf16x8*)(kb + r32 * KSTR + (16 * (s + 1) + 8 * h) * 2);
;                     kq[(s + 1) & 1][1] = *(const LAS bf16x8*)(kb + (32 + r32) * KSTR + (16 * (s + 1) + 8 * h) * 2);
;                     __builtin_amdgcn_sched_group_barrier(0x100, 2, 0);
;                 }
;                 s0 = __builtin_amdgcn_mfma_f32_32x32x16_bf16(kq[s & 1][0], qf[s], s == 0 ? zero16 : s0, 0, 0, 0);
;                 s1 = __builtin_amdgcn_mfma_f32_32x32x16_bf16(kq[s & 1][1], qf[s], s == 0 ? zero16 : s1, 0, 0, 0);
;                 __builtin_amdgcn_sched_group_barrier(0x008, 2, 0);
;             }
;             if (loc && A.mode == 1) {
;                 const int qc = 32 * (wid & 1) + r32;
;                 const int w0 = min(max(qc - 8, 0), 48);
;                 const int rbase = (A.a0 + t - A.a1 + 7) * 31;
; #pragma unroll
;                 for (int r = 0; r < 16; ++r) {
;                     const int kc = (r & 3) + 8 * (r >> 2) + 4 * h;
;                     { const int dc = min(max(kc - qc + 15, 0), 30); const bool ok = (unsigned)(kc - w0) < 16u; const float bv = rpbl[rbase + dc]; s0[r] = ok ? s0[r] + bv : -1e30f; }
;                     { const int kc2 = kc + 32; const int dc = min(max(kc2 - qc + 15, 0), 30); const bool ok = (unsigned)(kc2 - w0) < 16u; const float bv = rpbl[rbase + dc]; s1[r] = ok ? s1[r] + bv : -1e30f; }
;                 }
;             } else if (loc && A.mode == 2) {
;                 const int p0 = A.a0 + 64 * t;
;                 if (p0 < A.a1 + 31 - 128 || p0 + 63 > A.a1 + 128) {
;                     const int dbase = p0 - (A.a1 + r32);
; #pragma unroll
;                     for (int r = 0; r < 16; ++r) {
;                         const int kc = (r & 3) + 8 * (r >> 2) + 4 * h;
;                         s0[r] = ((unsigned)(dbase + kc + 128) > 256u) ? -1e30f : s0[r];
.LBB0_60:
	s_andn2_b64 vcc, exec, s[52:53]
	s_cbranch_vccnz .LBB0_135
	v_add3_u32 v0, s83, v177, v156
	ds_read_b128 v[2:5], v0
	ds_read_b128 v[6:9], v0 offset:4608
	ds_read_b128 v[10:13], v0 offset:32
	ds_read_b128 v[114:117], v0 offset:4640
	s_andn2_b64 vcc, exec, s[50:51]
	s_mov_b64 s[50:51], -1
	s_waitcnt lgkmcnt(0)
	v_mfma_f32_32x32x16_bf16 v[66:81], v[2:5], v[130:133], v[16:31]
	v_mfma_f32_32x32x16_bf16 v[82:97], v[6:9], v[130:133], v[16:31]
	ds_read_b128 v[2:5], v0 offset:64
	ds_read_b128 v[6:9], v0 offset:4672
	v_mfma_f32_32x32x16_bf16 v[66:81], v[10:13], v[134:137], v[66:81]
	v_mfma_f32_32x32x16_bf16 v[82:97], v[114:117], v[134:137], v[82:97]
	ds_read_b128 v[10:13], v0 offset:96
	ds_read_b128 v[114:117], v0 offset:4704
	s_waitcnt lgkmcnt(0)
	v_mfma_f32_32x32x16_bf16 v[66:81], v[2:5], v[138:141], v[66:81]
	v_mfma_f32_32x32x16_bf16 v[82:97], v[6:9], v[138:141], v[82:97]
	v_mfma_f32_32x32x16_bf16 v[66:81], v[10:13], v[142:145], v[66:81]
	v_mfma_f32_32x32x16_bf16 v[82:97], v[114:117], v[142:145], v[82:97]
	s_cbranch_vccz .LBB0_66
	s_and_b64 s[48:49], s[86:87], s[48:49]
	s_nop 8
	s_andn2_b64 vcc, exec, s[48:49]
	s_cbranch_vccnz .LBB0_65
	s_add_i32 s50, s55, s41
	s_cmp_lt_i32 s50, s63
	s_cselect_b64 s[48:49], -1, 0
	s_cmp_gt_i32 s50, s80
	s_cselect_b64 s[50:51], -1, 0
	s_or_b64 s[48:49], s[48:49], s[50:51]
	s_andn2_b64 vcc, exec, s[48:49]
	s_cbranch_vccnz .LBB0_65
	v_add_u32_e32 v0, s55, v159
	v_add_u32_e32 v2, 0xffffff7f, v0
	s_movk_i32 s48, 0xfefe
	v_cmp_lt_u32_e32 vcc, s48, v2
	v_add_u32_e32 v2, 0xffffff9f, v0
	s_nop 0
	v_cndmask_b32_e32 v66, v241, v66, vcc
	v_cmp_lt_u32_e32 vcc, s48, v2
	v_add_u32_e32 v2, 0xffffff80, v0
	s_nop 0
	v_cndmask_b32_e32 v82, v241, v82, vcc
	v_cmp_lt_u32_e32 vcc, s48, v2
	v_add_u32_e32 v2, 0xffffffa0, v0
	s_nop 0
	v_cndmask_b32_e32 v67, v241, v67, vcc
	v_cmp_lt_u32_e32 vcc, s48, v2
	v_add_u32_e32 v2, 0xffffff81, v0
	s_nop 0
	v_cndmask_b32_e32 v83, v241, v83, vcc
	v_cmp_lt_u32_e32 vcc, s48, v2
	v_add_u32_e32 v2, 0xffffffa1, v0
	s_nop 0
	v_cndmask_b32_e32 v68, v241, v68, vcc
	v_cmp_lt_u32_e32 vcc, s48, v2
	v_add_u32_e32 v2, 0xffffff82, v0
	s_nop 0
	v_cndmask_b32_e32 v84, v241, v84, vcc
	v_cmp_lt_u32_e32 vcc, s48, v2
	v_add_u32_e32 v2, 0xffffffa2, v0
	s_nop 0
	v_cndmask_b32_e32 v69, v241, v69, vcc
	v_cmp_lt_u32_e32 vcc, s48, v2
	v_add_u32_e32 v2, 0xffffff87, v0
	s_nop 0
	v_cndmask_b32_e32 v85, v241, v85, vcc
	v_cmp_lt_u32_e32 vcc, s48, v2
	v_add_u32_e32 v2, 0xffffffa7, v0
	s_nop 0
	v_cndmask_b32_e32 v70, v241, v70, vcc
	v_cmp_lt_u32_e32 vcc, s48, v2
	v_add_u32_e32 v2, 0xffffff88, v0
	s_nop 0
	v_cndmask_b32_e32 v86, v241, v86, vcc
	v_cmp_lt_u32_e32 vcc, s48, v2
	v_add_u32_e32 v2, 0xffffffa8, v0
	s_nop 0
	v_cndmask_b32_e32 v71, v241, v71, vcc
	v_cmp_lt_u32_e32 vcc, s48, v2
	v_add_u32_e32 v2, 0xffffff89, v0
	s_nop 0
	v_cndmask_b32_e32 v87, v241, v87, vcc
	v_cmp_lt_u32_e32 vcc, s48, v2
	v_add_u32_e32 v2, 0xffffffa9, v0
	s_nop 0
	v_cndmask_b32_e32 v72, v241, v72, vcc
	v_cmp_lt_u32_e32 vcc, s48, v2
	v_add_u32_e32 v2, 0xffffff8a, v0
	s_nop 0
	v_cndmask_b32_e32 v88, v241, v88, vcc
	v_cmp_lt_u32_e32 vcc, s48, v2
	v_add_u32_e32 v2, 0xffffffaa, v0
	s_nop 0
	v_cndmask_b32_e32 v73, v241, v73, vcc
	v_cmp_lt_u32_e32 vcc, s48, v2
	v_add_u32_e32 v2, 0xffffff8f, v0
	s_nop 0
	v_cndmask_b32_e32 v89, v241, v89, vcc
	v_cmp_lt_u32_e32 vcc, s48, v2
	v_add_u32_e32 v2, 0xffffffaf, v0
	s_nop 0
	v_cndmask_b32_e32 v74, v241, v74, vcc
	v_cmp_lt_u32_e32 vcc, s48, v2
	v_add_u32_e32 v2, 0xffffff90, v0
	s_nop 0
	v_cndmask_b32_e32 v90, v241, v90, vcc
	v_cmp_lt_u32_e32 vcc, s48, v2
	v_add_u32_e32 v2, 0xffffffb0, v0
	s_nop 0
	v_cndmask_b32_e32 v75, v241, v75, vcc
	v_cmp_lt_u32_e32 vcc, s48, v2
	v_add_u32_e32 v2, 0xffffff91, v0
	s_nop 0
	v_cndmask_b32_e32 v91, v241, v91, vcc
	v_cmp_lt_u32_e32 vcc, s48, v2
	v_add_u32_e32 v2, 0xffffffb1, v0
	s_nop 0
	v_cndmask_b32_e32 v76, v241, v76, vcc
	v_cmp_lt_u32_e32 vcc, s48, v2
	v_add_u32_e32 v2, 0xffffff92, v0
	s_nop 0
	v_cndmask_b32_e32 v92, v241, v92, vcc
	v_cmp_lt_u32_e32 vcc, s48, v2
	v_add_u32_e32 v2, 0xffffffb2, v0
	s_nop 0
	v_cndmask_b32_e32 v77, v241, v77, vcc
	v_cmp_lt_u32_e32 vcc, s48, v2
	v_add_u32_e32 v2, 0xffffff97, v0
	s_nop 0
	v_cndmask_b32_e32 v93, v241, v93, vcc
	v_cmp_lt_u32_e32 vcc, s48, v2
	v_add_u32_e32 v2, 0xffffffb7, v0
	s_nop 0
	v_cndmask_b32_e32 v78, v241, v78, vcc
	v_cmp_lt_u32_e32 vcc, s48, v2
	v_add_u32_e32 v2, 0xffffff98, v0
	s_nop 0
	v_cndmask_b32_e32 v94, v241, v94, vcc
	v_cmp_lt_u32_e32 vcc, s48, v2
	v_add_u32_e32 v2, 0xffffffb8, v0
	s_nop 0
	v_cndmask_b32_e32 v79, v241, v79, vcc
	v_cmp_lt_u32_e32 vcc, s48, v2
	v_add_u32_e32 v2, 0xffffff99, v0
	s_nop 0
	v_cndmask_b32_e32 v95, v241, v95, vcc
	v_cmp_lt_u32_e32 vcc, s48, v2
	v_add_u32_e32 v2, 0xffffffb9, v0
	s_nop 0
	v_cndmask_b32_e32 v80, v241, v80, vcc
	v_cmp_lt_u32_e32 vcc, s48, v2
	v_add_u32_e32 v2, 0xffffff9a, v0
	v_add_u32_e32 v0, 0xffffffba, v0
	v_cndmask_b32_e32 v96, v241, v96, vcc
	v_cmp_lt_u32_e32 vcc, s48, v2
	s_nop 1
	v_cndmask_b32_e32 v81, v241, v81, vcc
	v_cmp_lt_u32_e32 vcc, s48, v0
	s_nop 1
	v_cndmask_b32_e32 v97, v241, v97, vcc

; template <int DQ>
; __device__ __forceinline__ void attn_unit(LAS unsigned char* lds, const AttnDesc& A, int tid_in, int wid, int lane_in) {
;     ...
;             if (loc && A.mode == 1) {
;                 const int qc = 32 * (wid & 1) + r32;
;                 const int w0 = min(max(qc - 8, 0), 48);
;                 const int rbase = (A.a0 + t - A.a1 + 7) * 31;
; #pragma unroll
;                 for (int r = 0; r < 16; ++r) {
;                     const int kc = (r & 3) + 8 * (r >> 2) + 4 * h;
;                     { const int dc = min(max(kc - qc + 15, 0), 30); const bool ok = (unsigned)(kc - w0) < 16u; const float bv = rpbl[rbase + dc]; s0[r] = ok ? s0[r] + bv : -1e30f; }
;                     { const int kc2 = kc + 32; const int dc = min(max(kc2 - qc + 15, 0), 30); const bool ok = (unsigned)(kc2 - w0) < 16u; const float bv = rpbl[rbase + dc]; s1[r] = ok ? s1[r] + bv : -1e30f; }
;                 }
.LBB0_66:
	s_andn2_b64 vcc, exec, s[50:51]
	s_cbranch_vccnz .LBB0_132
	v_add_u32_e32 v0, s81, v178
	ds_read_b32 v114, v0 offset:43936
	v_add_u32_e32 v0, s81, v179
	ds_read_b32 v98, v0 offset:43876
	v_add_u32_e32 v0, s81, v180
	ds_read_b32 v115, v0 offset:43936
	v_add_u32_e32 v0, s81, v182
	ds_read_b32 v99, v0 offset:43876
	v_add_u32_e32 v0, s81, v183
	ds_read_b32 v116, v0 offset:43936
	v_add_u32_e32 v0, s81, v184
	ds_read_b32 v100, v0 offset:43876
	v_add_u32_e32 v0, s81, v185
	ds_read_b32 v117, v0 offset:43936
	v_add_u32_e32 v0, s81, v186
	ds_read_b32 v101, v0 offset:43876
	v_add_u32_e32 v0, s81, v187
	ds_read_b32 v118, v0 offset:43936
	v_add_u32_e32 v0, s81, v188
	ds_read_b32 v102, v0 offset:43876
	v_add_u32_e32 v0, s81, v189
	ds_read_b32 v119, v0 offset:43936
	v_add_u32_e32 v0, s81, v190
	ds_read_b32 v103, v0 offset:43876
	v_add_u32_e32 v0, s81, v191
	ds_read_b32 v120, v0 offset:43936
	v_add_u32_e32 v0, s81, v192
	ds_read_b32 v104, v0 offset:43876
	v_add_u32_e32 v0, s81, v193
	ds_read_b32 v121, v0 offset:43936
	s_waitcnt lgkmcnt(14)
	v_add_f32_e32 v66, v66, v114
	v_add_u32_e32 v0, s81, v194
	ds_read_b32 v105, v0 offset:43876
	s_waitcnt lgkmcnt(14)
	v_add_f32_e32 v82, v82, v98
	v_add_u32_e32 v0, s81, v195
	ds_read_b32 v122, v0 offset:43876
	s_waitcnt lgkmcnt(14)
	v_add_f32_e32 v67, v67, v115
	v_add_u32_e32 v0, s81, v196
	ds_read_b32 v106, v0 offset:43876
	s_waitcnt lgkmcnt(14)
	v_add_f32_e32 v83, v83, v99
	v_add_u32_e32 v0, s81, v197
	ds_read_b32 v123, v0 offset:43876
	s_waitcnt lgkmcnt(14)
	v_add_f32_e32 v68, v68, v116
	v_add_u32_e32 v0, s81, v198
	ds_read_b32 v107, v0 offset:43876
	s_waitcnt lgkmcnt(14)
	v_add_f32_e32 v84, v84, v100
	v_add_u32_e32 v0, s81, v199
	ds_read_b32 v124, v0 offset:43876
	s_waitcnt lgkmcnt(14)
	v_add_f32_e32 v69, v69, v117
	v_add_u32_e32 v0, s81, v200
	ds_read_b32 v108, v0 offset:43876
	s_waitcnt lgkmcnt(14)
	v_add_f32_e32 v85, v85, v101
	v_add_u32_e32 v0, s81, v201
	ds_read_b32 v125, v0 offset:43876
	s_waitcnt lgkmcnt(14)
	v_add_f32_e32 v70, v70, v118
	v_add_u32_e32 v0, s81, v202
	ds_read_b32 v109, v0 offset:43876
	s_waitcnt lgkmcnt(14)
	v_add_f32_e32 v86, v86, v102
	v_add_u32_e32 v0, s81, v203
	ds_read_b32 v126, v0 offset:43876
	s_waitcnt lgkmcnt(14)
	v_add_f32_e32 v71, v71, v119
	v_add_u32_e32 v0, s81, v204
	ds_read_b32 v110, v0 offset:43876
	s_waitcnt lgkmcnt(14)
	v_add_f32_e32 v87, v87, v103
	v_add_u32_e32 v0, s81, v205
	ds_read_b32 v127, v0 offset:43876
	s_waitcnt lgkmcnt(14)
	v_add_f32_e32 v72, v72, v120
	v_add_u32_e32 v0, s81, v206
	ds_read_b32 v111, v0 offset:43876
	s_waitcnt lgkmcnt(14)
	v_add_f32_e32 v88, v88, v104
	v_add_u32_e32 v0, s81, v207
	ds_read_b32 v128, v0 offset:43876
	s_waitcnt lgkmcnt(14)
	v_add_f32_e32 v73, v73, v121
	v_add_u32_e32 v0, s81, v208
	ds_read_b32 v112, v0 offset:43876
	s_waitcnt lgkmcnt(14)
	v_add_f32_e32 v89, v89, v105
	v_add_u32_e32 v0, s81, v209
	ds_read_b32 v129, v0 offset:43876
	s_waitcnt lgkmcnt(14)
	v_add_f32_e32 v74, v74, v122
	v_add_u32_e32 v0, s81, v210
	ds_read_b32 v113, v0 offset:43876
	s_waitcnt lgkmcnt(14)
	v_add_f32_e32 v90, v90, v106
	s_waitcnt lgkmcnt(13)
	v_add_f32_e32 v75, v75, v123
	s_waitcnt lgkmcnt(12)
	v_add_f32_e32 v91, v91, v107
	s_waitcnt lgkmcnt(11)
	v_add_f32_e32 v76, v76, v124
	s_waitcnt lgkmcnt(10)
	v_add_f32_e32 v92, v92, v108
	s_waitcnt lgkmcnt(9)
	v_add_f32_e32 v77, v77, v125
	s_waitcnt lgkmcnt(8)
	v_add_f32_e32 v93, v93, v109
	s_waitcnt lgkmcnt(7)
	v_add_f32_e32 v78, v78, v126
	s_waitcnt lgkmcnt(6)
	v_add_f32_e32 v94, v94, v110
	s_waitcnt lgkmcnt(5)
	v_add_f32_e32 v79, v79, v127
	s_waitcnt lgkmcnt(4)
	v_add_f32_e32 v95, v95, v111
	s_waitcnt lgkmcnt(3)
	v_add_f32_e32 v80, v80, v128
	s_waitcnt lgkmcnt(2)
	v_add_f32_e32 v96, v96, v112
	s_waitcnt lgkmcnt(1)
	v_add_f32_e32 v81, v81, v129
	s_waitcnt lgkmcnt(0)
	v_add_f32_e32 v97, v97, v113
